# stack + hyena filter-odd lean trips prefetch the next trip's loads
# speedup vs baseline: 1.0068x; 1.0068x over previous
.Lhyo_lean:
	s_waitcnt vmcnt(0)
	s_mov_b32 s9, 0x7f800000
	v_sub_f32_e32 v97, v66, v77
	v_sub_f32_e32 v98, v67, v72
	v_sub_f32_e32 v99, v68, v71
	v_sub_f32_e32 v100, v69, v70
	s_movk_i32 s0, 0xe000
	s_mov_b32 s1, -1
	v_lshl_add_u64 v[78:79], v[78:79], 0, s[0:1]
	s_mov_b64 s[0:1], 0x2000
	v_lshl_add_u64 v[80:81], v[80:81], 0, s[0:1]
	v_add_u32_e32 v0, 0xfffff800, v0
	s_movk_i32 s0, 0x37ff
	v_cmp_lt_i32_e32 vcc, s0, v76
	v_add_u32_e32 v76, 0x800, v76
	s_or_b64 s[24:25], vcc, s[24:25]
	s_cbranch_vccnz .Lhyo_nopf
	v_lshl_add_u64 v[68:69], s[76:77], 0, v[78:79]
	v_add_co_u32_e32 v70, vcc, 0xf000, v68
	v_lshl_add_u64 v[66:67], s[76:77], 0, v[80:81]
	s_nop 0
	v_addc_co_u32_e32 v71, vcc, 0, v69, vcc
	global_load_dwordx4 v[66:69], v[66:67], off
	s_nop 0
	global_load_dwordx3 v[70:72], v[70:71], off offset:4084
	v_lshl_add_u64 v[94:95], v[0:1], 2, s[54:55]
	global_load_dword v77, v[94:95], off
.Lhyo_nopf:
	v_mul_f32_e32 v82, 0x3f6c835e, v150
	v_mul_f32_e32 v84, 0x3f6c835e, v151
	v_mul_f32_e32 v86, 0x3f6c835e, v152
	v_mul_f32_e32 v88, 0x3f6c835e, v153
	v_mul_f32_e32 v89, 0x3f6c835e, v154
	v_mul_f32_e32 v90, 0x3f6c835e, v155
	v_mul_f32_e32 v91, 0x3f6c835e, v156
	v_mul_f32_e32 v92, 0x3f6c835e, v157
	v_fmamk_f32 v84, v150, 0x3ec3ef15, v84
	v_fmamk_f32 v150, v151, 0xbec3ef15, v82
	v_mov_b32_e32 v151, v84
	v_fmamk_f32 v88, v152, 0x3ec3ef15, v88
	v_fmamk_f32 v152, v153, 0xbec3ef15, v86
	v_mov_b32_e32 v153, v88
	v_fmamk_f32 v90, v154, 0x3ec3ef15, v90
	v_fmamk_f32 v154, v155, 0xbec3ef15, v89
	v_mov_b32_e32 v155, v90
	v_fmamk_f32 v92, v156, 0x3ec3ef15, v92
	v_fmamk_f32 v156, v157, 0xbec3ef15, v91
	v_mov_b32_e32 v157, v92
	v_mul_f32_e32 v102, v150, v97
	v_mul_f32_e64 v103, v151, -v97
	v_mul_f32_e32 v104, v152, v98
	v_mul_f32_e64 v105, v153, -v98
	v_mul_f32_e32 v88, v154, v99
	v_mul_f32_e64 v89, v155, -v99
	v_mul_f32_e32 v90, v156, v100
	v_mul_f32_e64 v91, v157, -v100
	ds_write_b128 v73, v[102:105]
	ds_write_b128 v73, v[88:91] offset:16
	v_add_u32_e32 v73, 0x4000, v73
	s_andn2_b64 exec, exec, s[24:25]
	s_cbranch_execz .LBB0_1057
	s_branch .Lhyo_lean
